# v39 + v_permlane32_swap instead of ds_bpermute xor-32 exchanges in attention A/B softmax max and the indexer score reduce
# baseline (speedup 1.0000x reference)
.LBB0_598:
	v_lshl_add_u32 v35, 2, v127, -1
	v_cmp_lt_i32_e32 vcc, -1, v127
	v_add_u32_e32 v34, 0xffffff81, v127
	s_movk_i32 s11, 0x9f
	v_cndmask_b32_e32 v35, 0, v35, vcc
	v_cmp_gt_i32_e32 vcc, 31, v127
	v_lshlrev_b32_e64 v34, v34, -1
	s_nop 0
	v_cndmask_b32_e32 v35, -1, v35, vcc
	v_cmp_gt_i32_e32 vcc, s11, v127
	s_movk_i32 s11, 0x7f
	s_nop 0
	v_cndmask_b32_e32 v34, 0, v34, vcc
	v_cmp_lt_i32_e32 vcc, s11, v127
	s_nop 1
	v_cndmask_b32_e32 v34, -1, v34, vcc
	v_and_b32_e32 v142, v35, v34
	ds_read_b128 v[34:37], v128
	ds_read_b128 v[130:133], v128 offset:32
	ds_read_b128 v[134:137], v128 offset:64
	ds_read_b128 v[138:141], v128 offset:96
	s_waitcnt lgkmcnt(3)
	v_mfma_f32_32x32x16_bf16 v[34:49], v[34:37], v[90:93], 0
	s_waitcnt lgkmcnt(2)
	v_mfma_f32_32x32x16_bf16 v[34:49], v[130:133], v[94:97], v[34:49]
	s_waitcnt lgkmcnt(1)
	v_mfma_f32_32x32x16_bf16 v[34:49], v[134:137], v[98:101], v[34:49]
	v_lshrrev_b32_e32 v134, v145, v142
	v_bfe_i32 v130, v134, 0, 1
	s_waitcnt lgkmcnt(0)
	v_mfma_f32_32x32x16_bf16 v[34:49], v[138:141], v[102:105], v[34:49]
	s_nop 11
	v_bitop3_b32 v130, v34, s70, v130 bitop3:0xe4
	v_bfe_i32 v34, v134, 1, 1
	v_bitop3_b32 v34, v35, s70, v34 bitop3:0xe4
	v_bfe_i32 v35, v134, 2, 1
	v_bitop3_b32 v131, v36, s70, v35 bitop3:0xe4
	v_bfe_i32 v35, v134, 3, 1
	v_max3_f32 v132, v130, s70, v34
	v_bitop3_b32 v35, v37, s70, v35 bitop3:0xe4
	v_bfe_i32 v37, v134, 8, 1
	v_max3_f32 v36, v132, v131, v35
	v_bitop3_b32 v132, v38, s70, v37 bitop3:0xe4
	v_bfe_i32 v37, v134, 9, 1
	v_bitop3_b32 v38, v39, s70, v37 bitop3:0xe4
	v_max3_f32 v37, v36, v132, v38
	v_bfe_i32 v36, v134, 10, 1
	v_bitop3_b32 v39, v40, s70, v36 bitop3:0xe4
	v_bfe_i32 v36, v134, 11, 1
	v_bitop3_b32 v36, v41, s70, v36 bitop3:0xe4
	v_max3_f32 v41, v37, v39, v36
	v_bfe_i32 v37, v134, 16, 1
	v_bitop3_b32 v37, v42, s70, v37 bitop3:0xe4
	v_bfe_i32 v42, v134, 18, 1
	v_bfe_i32 v40, v134, 17, 1
	v_bitop3_b32 v133, v44, s70, v42 bitop3:0xe4
	v_bfe_i32 v42, v134, 19, 1
	v_bitop3_b32 v40, v43, s70, v40 bitop3:0xe4
	v_bitop3_b32 v44, v45, s70, v42 bitop3:0xe4
	v_bfe_i32 v42, v134, 24, 1
	v_max3_f32 v41, v41, v37, v40
	v_bitop3_b32 v45, v46, s70, v42 bitop3:0xe4
	v_bfe_i32 v42, v134, 25, 1
	v_max3_f32 v41, v41, v133, v44
	v_bitop3_b32 v42, v47, s70, v42 bitop3:0xe4
	v_max3_f32 v46, v41, v45, v42
	v_bfe_i32 v41, v134, 26, 1
	v_bitop3_b32 v43, v48, s70, v41 bitop3:0xe4
	v_bfe_i32 v41, v134, 27, 1
	v_bitop3_b32 v41, v49, s70, v41 bitop3:0xe4
	v_max3_f32 v46, v46, v43, v41
	v_mov_b32_e32 v47, v46
	s_nop 1
	v_permlane32_swap_b32_e32 v47, v46
	v_max_f32_e32 v46, v46, v47
	v_add_f32_e32 v47, 0x41000000, v126
	v_cmp_gt_f32_e32 vcc, v46, v47
	s_cbranch_vccz .LBB0_597
	v_max_f32_e32 v46, v46, v46
	v_max_f32_e32 v47, v126, v126
	v_max_f32_e32 v47, v47, v46
	v_cmp_neq_f32_e32 vcc, s70, v47
	s_nop 1
	v_cndmask_b32_e32 v46, 0, v47, vcc
	v_sub_f32_e32 v46, v126, v46
	v_exp_f32_e32 v46, v46
	v_mov_b32_e32 v126, v47
	v_mul_f32_e32 v125, v125, v46
	v_pk_mul_f32 v[16:17], v[16:17], v[46:47] op_sel_hi:[1,0]
	v_pk_mul_f32 v[14:15], v[14:15], v[46:47] op_sel_hi:[1,0]
	v_pk_mul_f32 v[12:13], v[12:13], v[46:47] op_sel_hi:[1,0]
	v_pk_mul_f32 v[10:11], v[10:11], v[46:47] op_sel_hi:[1,0]
	v_pk_mul_f32 v[8:9], v[8:9], v[46:47] op_sel_hi:[1,0]
	v_pk_mul_f32 v[6:7], v[6:7], v[46:47] op_sel_hi:[1,0]
	v_pk_mul_f32 v[4:5], v[4:5], v[46:47] op_sel_hi:[1,0]
	v_pk_mul_f32 v[2:3], v[2:3], v[46:47] op_sel_hi:[1,0]
	v_pk_mul_f32 v[32:33], v[32:33], v[46:47] op_sel_hi:[1,0]
	v_pk_mul_f32 v[30:31], v[30:31], v[46:47] op_sel_hi:[1,0]
	v_pk_mul_f32 v[28:29], v[28:29], v[46:47] op_sel_hi:[1,0]
	v_pk_mul_f32 v[26:27], v[26:27], v[46:47] op_sel_hi:[1,0]
	v_pk_mul_f32 v[24:25], v[24:25], v[46:47] op_sel_hi:[1,0]
	v_pk_mul_f32 v[22:23], v[22:23], v[46:47] op_sel_hi:[1,0]
	v_pk_mul_f32 v[20:21], v[20:21], v[46:47] op_sel_hi:[1,0]
	v_pk_mul_f32 v[18:19], v[18:19], v[46:47] op_sel_hi:[1,0]
	s_branch .LBB0_597

.LBB0_621:
	s_and_b32 s26, s26, 1
	s_mul_i32 s27, s26, 0x4400
	v_add3_u32 v0, v185, s27, v186
	ds_read_b128 v[4:7], v0
	ds_read_b128 v[8:11], v0 offset:32
	ds_read_b128 v[12:15], v0 offset:8704
	ds_read_b128 v[196:199], v0 offset:8736
	s_waitcnt lgkmcnt(3)
	v_mfma_f32_32x32x16_bf16 v[96:111], v[4:7], v[152:155], 0
	s_waitcnt lgkmcnt(1)
	v_mfma_f32_32x32x16_bf16 v[80:95], v[12:15], v[152:155], 0
	v_mfma_f32_32x32x16_bf16 v[96:111], v[8:11], v[136:139], v[96:111]
	s_waitcnt lgkmcnt(0)
	v_mfma_f32_32x32x16_bf16 v[80:95], v[196:199], v[136:139], v[80:95]
	ds_read_b128 v[4:7], v0 offset:64
	ds_read_b128 v[8:11], v0 offset:96
	ds_read_b128 v[12:15], v0 offset:8768
	ds_read_b128 v[196:199], v0 offset:8800
	s_waitcnt lgkmcnt(3)
	v_mfma_f32_32x32x16_bf16 v[96:111], v[4:7], v[148:151], v[96:111]
	s_waitcnt lgkmcnt(1)
	v_mfma_f32_32x32x16_bf16 v[80:95], v[12:15], v[148:151], v[80:95]
	v_mfma_f32_32x32x16_bf16 v[96:111], v[8:11], v[132:135], v[96:111]
	s_waitcnt lgkmcnt(0)
	v_mfma_f32_32x32x16_bf16 v[80:95], v[196:199], v[132:135], v[80:95]
	ds_read_b128 v[4:7], v0 offset:128
	ds_read_b128 v[8:11], v0 offset:160
	ds_read_b128 v[12:15], v0 offset:8832
	ds_read_b128 v[196:199], v0 offset:8864
	s_waitcnt lgkmcnt(3)
	v_mfma_f32_32x32x16_bf16 v[96:111], v[4:7], v[144:147], v[96:111]
	s_waitcnt lgkmcnt(1)
	v_mfma_f32_32x32x16_bf16 v[80:95], v[12:15], v[144:147], v[80:95]
	v_mfma_f32_32x32x16_bf16 v[96:111], v[8:11], v[128:131], v[96:111]
	s_waitcnt lgkmcnt(0)
	v_mfma_f32_32x32x16_bf16 v[80:95], v[196:199], v[128:131], v[80:95]
	ds_read_b128 v[4:7], v0 offset:192
	ds_read_b128 v[8:11], v0 offset:224
	ds_read_b128 v[12:15], v0 offset:8896
	ds_read_b128 v[196:199], v0 offset:8928
	v_lshrrev_b32_e32 v0, v187, v166
	s_waitcnt lgkmcnt(3)
	v_mfma_f32_32x32x16_bf16 v[96:111], v[4:7], v[140:143], v[96:111]
	v_bfe_i32 v5, v0, 2, 1
	v_bfe_i32 v4, v0, 0, 1
	s_waitcnt lgkmcnt(1)
	v_mfma_f32_32x32x16_bf16 v[80:95], v[12:15], v[140:143], v[80:95]
	v_mfma_f32_32x32x16_bf16 v[96:111], v[8:11], v[156:159], v[96:111]
	s_waitcnt lgkmcnt(0)
	v_mfma_f32_32x32x16_bf16 v[80:95], v[196:199], v[156:159], v[80:95]
	s_nop 9
	v_bitop3_b32 v198, v98, s70, v5 bitop3:0xe4
	v_bfe_i32 v5, v0, 3, 1
	v_bitop3_b32 v199, v99, s70, v5 bitop3:0xe4
	v_bfe_i32 v5, v0, 8, 1
	v_bitop3_b32 v200, v100, s70, v5 bitop3:0xe4
	v_bfe_i32 v5, v0, 9, 1
	v_bitop3_b32 v201, v101, s70, v5 bitop3:0xe4
	v_bfe_i32 v5, v0, 10, 1
	v_bitop3_b32 v196, v96, s70, v4 bitop3:0xe4
	v_bfe_i32 v4, v0, 1, 1
	v_bitop3_b32 v202, v102, s70, v5 bitop3:0xe4
	v_bfe_i32 v5, v0, 11, 1
	v_bitop3_b32 v197, v97, s70, v4 bitop3:0xe4
	v_bitop3_b32 v166, v103, s70, v5 bitop3:0xe4
	v_bfe_i32 v5, v0, 16, 1
	v_max3_f32 v4, v196, s70, v197
	v_bitop3_b32 v100, v104, s70, v5 bitop3:0xe4
	v_bfe_i32 v5, v0, 17, 1
	v_max3_f32 v4, v4, v198, v199
	v_bitop3_b32 v101, v105, s70, v5 bitop3:0xe4
	v_bfe_i32 v5, v0, 18, 1
	v_max3_f32 v4, v4, v200, v201
	v_bitop3_b32 v98, v106, s70, v5 bitop3:0xe4
	v_bfe_i32 v5, v0, 19, 1
	v_max3_f32 v4, v4, v202, v166
	v_bitop3_b32 v102, v107, s70, v5 bitop3:0xe4
	v_bfe_i32 v5, v0, 24, 1
	v_max3_f32 v4, v4, v100, v101
	v_bitop3_b32 v103, v108, s70, v5 bitop3:0xe4
	v_bfe_i32 v5, v0, 25, 1
	v_max3_f32 v4, v4, v98, v102
	v_bitop3_b32 v99, v109, s70, v5 bitop3:0xe4
	v_bfe_i32 v5, v0, 26, 1
	v_bfe_i32 v0, v0, 27, 1
	v_max3_f32 v4, v4, v103, v99
	v_bitop3_b32 v104, v110, s70, v5 bitop3:0xe4
	v_bitop3_b32 v97, v111, s70, v0 bitop3:0xe4
	v_lshrrev_b32_e32 v105, v187, v167
	v_max3_f32 v0, v4, v104, v97
	v_bfe_i32 v4, v105, 0, 1
	v_bitop3_b32 v96, v80, s70, v4 bitop3:0xe4
	v_bfe_i32 v4, v105, 1, 1
	v_bitop3_b32 v81, v81, s70, v4 bitop3:0xe4
	v_bfe_i32 v4, v105, 2, 1
	v_bitop3_b32 v14, v82, s70, v4 bitop3:0xe4
	v_bfe_i32 v4, v105, 3, 1
	v_bitop3_b32 v15, v83, s70, v4 bitop3:0xe4
	v_bfe_i32 v4, v105, 8, 1
	v_bitop3_b32 v80, v84, s70, v4 bitop3:0xe4
	v_bfe_i32 v4, v105, 9, 1
	v_bitop3_b32 v12, v85, s70, v4 bitop3:0xe4
	v_bfe_i32 v4, v105, 10, 1
	v_bitop3_b32 v13, v86, s70, v4 bitop3:0xe4
	v_bfe_i32 v4, v105, 11, 1
	v_bitop3_b32 v11, v87, s70, v4 bitop3:0xe4
	v_bfe_i32 v4, v105, 16, 1
	v_max3_f32 v0, v0, v96, v81
	v_bitop3_b32 v9, v88, s70, v4 bitop3:0xe4
	v_bfe_i32 v4, v105, 17, 1
	v_max3_f32 v0, v0, v14, v15
	v_bitop3_b32 v10, v89, s70, v4 bitop3:0xe4
	v_bfe_i32 v4, v105, 18, 1
	v_max3_f32 v0, v0, v80, v12
	v_bitop3_b32 v6, v90, s70, v4 bitop3:0xe4
	v_bfe_i32 v4, v105, 19, 1
	v_max3_f32 v0, v0, v13, v11
	v_bitop3_b32 v7, v91, s70, v4 bitop3:0xe4
	v_bfe_i32 v4, v105, 24, 1
	v_max3_f32 v0, v0, v9, v10
	v_bitop3_b32 v8, v92, s70, v4 bitop3:0xe4
	v_bfe_i32 v4, v105, 25, 1
	v_max3_f32 v0, v0, v6, v7
	v_bitop3_b32 v4, v93, s70, v4 bitop3:0xe4
	v_max3_f32 v82, v0, v8, v4
	v_bfe_i32 v0, v105, 26, 1
	v_bitop3_b32 v5, v94, s70, v0 bitop3:0xe4
	v_bfe_i32 v0, v105, 27, 1
	v_bitop3_b32 v0, v95, s70, v0 bitop3:0xe4
	v_max3_f32 v82, v82, v5, v0
	v_mov_b32_e32 v83, v82
	s_nop 1
	v_permlane32_swap_b32_e32 v83, v82
	v_max_f32_e32 v82, v82, v83
	v_add_f32_e32 v83, 0x41000000, v183
	v_cmp_gt_f32_e32 vcc, v82, v83
	s_cbranch_vccz .LBB0_623
	v_max_f32_e32 v82, v82, v82
	v_max_f32_e32 v83, v183, v183
	v_max_f32_e32 v83, v83, v82
	v_cmp_neq_f32_e32 vcc, s70, v83
	s_nop 1
	v_cndmask_b32_e32 v82, 0, v83, vcc
	v_sub_f32_e32 v82, v183, v82
	v_exp_f32_e32 v82, v82
	v_mov_b32_e32 v183, v83
	v_mul_f32_e32 v182, v182, v82
	v_pk_mul_f32 v[78:79], v[78:79], v[82:83] op_sel_hi:[1,0]
	v_pk_mul_f32 v[76:77], v[76:77], v[82:83] op_sel_hi:[1,0]
	v_pk_mul_f32 v[74:75], v[74:75], v[82:83] op_sel_hi:[1,0]
	v_pk_mul_f32 v[72:73], v[72:73], v[82:83] op_sel_hi:[1,0]
	v_pk_mul_f32 v[70:71], v[70:71], v[82:83] op_sel_hi:[1,0]
	v_pk_mul_f32 v[68:69], v[68:69], v[82:83] op_sel_hi:[1,0]
	v_pk_mul_f32 v[66:67], v[66:67], v[82:83] op_sel_hi:[1,0]
	v_pk_mul_f32 v[64:65], v[64:65], v[82:83] op_sel_hi:[1,0]
	v_pk_mul_f32 v[62:63], v[62:63], v[82:83] op_sel_hi:[1,0]
	v_pk_mul_f32 v[60:61], v[60:61], v[82:83] op_sel_hi:[1,0]
	v_pk_mul_f32 v[58:59], v[58:59], v[82:83] op_sel_hi:[1,0]
	v_pk_mul_f32 v[56:57], v[56:57], v[82:83] op_sel_hi:[1,0]
	v_pk_mul_f32 v[54:55], v[54:55], v[82:83] op_sel_hi:[1,0]
	v_pk_mul_f32 v[52:53], v[52:53], v[82:83] op_sel_hi:[1,0]
	v_pk_mul_f32 v[50:51], v[50:51], v[82:83] op_sel_hi:[1,0]
	v_pk_mul_f32 v[48:49], v[48:49], v[82:83] op_sel_hi:[1,0]
	v_pk_mul_f32 v[46:47], v[46:47], v[82:83] op_sel_hi:[1,0]
	v_pk_mul_f32 v[44:45], v[44:45], v[82:83] op_sel_hi:[1,0]
	v_pk_mul_f32 v[42:43], v[42:43], v[82:83] op_sel_hi:[1,0]
	v_pk_mul_f32 v[40:41], v[40:41], v[82:83] op_sel_hi:[1,0]
	v_pk_mul_f32 v[38:39], v[38:39], v[82:83] op_sel_hi:[1,0]
	v_pk_mul_f32 v[36:37], v[36:37], v[82:83] op_sel_hi:[1,0]
	v_pk_mul_f32 v[34:35], v[34:35], v[82:83] op_sel_hi:[1,0]
	v_pk_mul_f32 v[32:33], v[32:33], v[82:83] op_sel_hi:[1,0]
	v_pk_mul_f32 v[30:31], v[30:31], v[82:83] op_sel_hi:[1,0]
	v_pk_mul_f32 v[28:29], v[28:29], v[82:83] op_sel_hi:[1,0]
	v_pk_mul_f32 v[26:27], v[26:27], v[82:83] op_sel_hi:[1,0]
	v_pk_mul_f32 v[24:25], v[24:25], v[82:83] op_sel_hi:[1,0]
	v_pk_mul_f32 v[22:23], v[22:23], v[82:83] op_sel_hi:[1,0]
	v_pk_mul_f32 v[20:21], v[20:21], v[82:83] op_sel_hi:[1,0]
	v_pk_mul_f32 v[18:19], v[18:19], v[82:83] op_sel_hi:[1,0]
	v_pk_mul_f32 v[16:17], v[16:17], v[82:83] op_sel_hi:[1,0]

.LBB0_649:
	s_barrier
	s_waitcnt vmcnt(2)
	ds_write_b128 v0, v[70:73]
	s_waitcnt lgkmcnt(0)
	s_barrier
	ds_read_b128 v[2:5], v126
	ds_read_b128 v[70:73], v126 offset:32
	s_waitcnt lgkmcnt(1)
	v_mfma_f32_32x32x16_bf16 v[18:33], v[34:37], v[2:5], 0
	ds_read_b128 v[2:5], v126 offset:4608
	ds_read_b128 v[128:131], v126 offset:4640
	s_add_i32 s6, s1, 4
	s_min_u32 s6, s6, s0
	s_lshl_b32 s52, s6, 6
	s_lshl_b64 s[6:7], s[52:53], 7
	s_add_i32 s1, s1, 1
	s_cmp_lg_u32 s0, s1
	s_waitcnt lgkmcnt(1)
	v_mfma_f32_32x32x16_bf16 v[2:17], v[34:37], v[2:5], 0
	v_mfma_f32_32x32x16_bf16 v[18:33], v[38:41], v[70:73], v[18:33]
	s_waitcnt lgkmcnt(0)
	v_mfma_f32_32x32x16_bf16 v[2:17], v[38:41], v[128:131], v[2:17]
	ds_read_b128 v[70:73], v126 offset:64
	ds_read_b128 v[128:131], v126 offset:96
	s_waitcnt lgkmcnt(1)
	v_mfma_f32_32x32x16_bf16 v[18:33], v[42:45], v[70:73], v[18:33]
	ds_read_b128 v[70:73], v126 offset:4672
	ds_read_b128 v[132:135], v126 offset:4704
	s_waitcnt lgkmcnt(1)
	v_mfma_f32_32x32x16_bf16 v[2:17], v[42:45], v[70:73], v[2:17]
	s_waitcnt vmcnt(1)
	v_mov_b64_e32 v[72:73], v[68:69]
	v_mov_b64_e32 v[70:71], v[66:67]
	s_waitcnt vmcnt(0)
	v_mov_b64_e32 v[66:67], v[74:75]
	v_mov_b64_e32 v[68:69], v[76:77]
	v_lshl_add_u64 v[74:75], v[90:91], 0, s[6:7]
	global_load_dwordx4 v[74:77], v[74:75], off
	v_mfma_f32_32x32x16_bf16 v[18:33], v[46:49], v[128:131], v[18:33]
	s_waitcnt lgkmcnt(0)
	v_mfma_f32_32x32x16_bf16 v[2:17], v[46:49], v[132:135], v[2:17]
	s_nop 9
	v_max_f32_e32 v18, v18, v18
	v_max_f32_e32 v26, v26, v26
	v_max_f32_e32 v19, v19, v19
	v_max_f32_e32 v27, v27, v27
	v_max_f32_e32 v18, 0, v18
	v_max_f32_e32 v26, 0, v26
	v_max_f32_e32 v20, v20, v20
	v_max_f32_e32 v2, v2, v2
	v_max_f32_e32 v10, v10, v10
	v_max_f32_e32 v3, v3, v3
	v_max_f32_e32 v11, v11, v11
	v_max_f32_e32 v2, 0, v2
	v_max_f32_e32 v10, 0, v10
	v_max_f32_e32 v28, v28, v28
	v_max_f32_e32 v4, v4, v4
	v_max_f32_e32 v12, v12, v12
	v_max_f32_e32 v19, 0, v19
	v_max_f32_e32 v27, 0, v27
	v_max_f32_e32 v3, 0, v3
	v_max_f32_e32 v11, 0, v11
	v_fma_f32 v18, v50, v18, 0
	v_fma_f32 v26, v58, v26, 0
	v_fma_f32 v2, v50, v2, 0
	v_fma_f32 v10, v58, v10, 0
	v_max_f32_e32 v21, v21, v21
	v_max_f32_e32 v29, v29, v29
	v_max_f32_e32 v5, v5, v5
	v_max_f32_e32 v13, v13, v13
	v_max_f32_e32 v20, 0, v20
	v_max_f32_e32 v28, 0, v28
	v_max_f32_e32 v4, 0, v4
	v_max_f32_e32 v12, 0, v12
	v_fmac_f32_e32 v18, v51, v19
	v_fmac_f32_e32 v26, v59, v27
	v_fmac_f32_e32 v2, v51, v3
	v_fmac_f32_e32 v10, v59, v11
	v_max_f32_e32 v22, v22, v22
	v_max_f32_e32 v30, v30, v30
	v_max_f32_e32 v6, v6, v6
	v_max_f32_e32 v14, v14, v14
	v_max_f32_e32 v21, 0, v21
	v_max_f32_e32 v29, 0, v29
	v_max_f32_e32 v5, 0, v5
	v_max_f32_e32 v13, 0, v13
	v_fmac_f32_e32 v18, v52, v20
	v_fmac_f32_e32 v26, v60, v28
	v_fmac_f32_e32 v2, v52, v4
	v_fmac_f32_e32 v10, v60, v12
	v_max_f32_e32 v23, v23, v23
	v_max_f32_e32 v31, v31, v31
	v_max_f32_e32 v7, v7, v7
	v_max_f32_e32 v15, v15, v15
	v_max_f32_e32 v22, 0, v22
	v_max_f32_e32 v30, 0, v30
	v_max_f32_e32 v6, 0, v6
	v_max_f32_e32 v14, 0, v14
	v_fmac_f32_e32 v18, v53, v21
	v_fmac_f32_e32 v26, v61, v29
	v_fmac_f32_e32 v2, v53, v5
	v_fmac_f32_e32 v10, v61, v13
	v_max_f32_e32 v24, v24, v24
	v_max_f32_e32 v32, v32, v32
	v_max_f32_e32 v8, v8, v8
	v_max_f32_e32 v16, v16, v16
	v_max_f32_e32 v23, 0, v23
	v_max_f32_e32 v31, 0, v31
	v_max_f32_e32 v7, 0, v7
	v_max_f32_e32 v15, 0, v15
	v_fmac_f32_e32 v18, v54, v22
	v_fmac_f32_e32 v26, v62, v30
	v_fmac_f32_e32 v2, v54, v6
	v_fmac_f32_e32 v10, v62, v14
	v_max_f32_e32 v25, v25, v25
	v_max_f32_e32 v33, v33, v33
	v_max_f32_e32 v9, v9, v9
	v_max_f32_e32 v17, v17, v17
	v_max_f32_e32 v24, 0, v24
	v_max_f32_e32 v32, 0, v32
	v_max_f32_e32 v8, 0, v8
	v_max_f32_e32 v16, 0, v16
	v_fmac_f32_e32 v18, v55, v23
	v_fmac_f32_e32 v26, v63, v31
	v_fmac_f32_e32 v2, v55, v7
	v_fmac_f32_e32 v10, v63, v15
	v_max_f32_e32 v25, 0, v25
	v_max_f32_e32 v33, 0, v33
	v_max_f32_e32 v9, 0, v9
	v_max_f32_e32 v17, 0, v17
	v_fmac_f32_e32 v18, v56, v24
	v_fmac_f32_e32 v26, v64, v32
	v_fmac_f32_e32 v2, v56, v8
	v_fmac_f32_e32 v10, v64, v16
	v_fmac_f32_e32 v18, v57, v25
	v_fmac_f32_e32 v26, v65, v33
	v_fmac_f32_e32 v2, v57, v9
	v_fmac_f32_e32 v10, v65, v17
	s_nop 1
	v_permlane32_swap_b32_e32 v18, v26
	v_permlane32_swap_b32_e32 v2, v10
	v_add_f32_e32 v3, v18, v26
	v_add_f32_e32 v2, v2, v10
	ds_write2_b32 v127, v3, v2 offset1:32
	v_add_u32_e32 v127, 0x100, v127
	s_cbranch_scc1 .LBB0_649
	s_mov_b32 s52, 0
	s_mov_b64 s[64:65], -1
	s_branch .LBB0_652
